# scan hazard-slot fill + aligned scan loops; retention code placed on a 128-byte boundary
# baseline (speedup 1.0000x reference)
; DI void scan_item(const Params& p, int l, bool ctx_out, int item, char* smem) {
;     ...
;     }
;     __syncthreads();
;   }
;     ...
; }
.Lscan_exit:
	v_readlane_b32 s0, v255, 0
	v_readlane_b32 s1, v255, 1
	v_readlane_b32 s2, v255, 2
	v_readlane_b32 s3, v255, 3
	v_readlane_b32 s4, v255, 4
	v_readlane_b32 s5, v255, 5
	v_readlane_b32 s6, v255, 6
	v_readlane_b32 s7, v255, 7
	v_readlane_b32 s8, v255, 8
	v_readlane_b32 s9, v255, 9
	v_readlane_b32 s10, v255, 10
	v_readlane_b32 s11, v255, 11
	v_readlane_b32 s12, v255, 12
	v_readlane_b32 s13, v255, 13
	v_readlane_b32 s14, v255, 14
	v_readlane_b32 s15, v255, 15
	v_readlane_b32 s16, v255, 16
	v_readlane_b32 s17, v255, 17
	v_readlane_b32 s18, v255, 18
	v_readlane_b32 s19, v255, 19
	v_readlane_b32 s20, v255, 20
	v_readlane_b32 s21, v255, 21
	v_readlane_b32 s22, v255, 22
	v_readlane_b32 s23, v255, 23
	v_readlane_b32 s24, v255, 24
	v_readlane_b32 s25, v255, 25
	v_readlane_b32 s26, v255, 26
	v_readlane_b32 s27, v255, 27
	v_readlane_b32 s28, v255, 28
	v_readlane_b32 s29, v255, 29
	v_readlane_b32 s30, v255, 30
	v_readlane_b32 s31, v255, 31
	v_readlane_b32 s32, v255, 32
	v_readlane_b32 s33, v255, 33
	v_readlane_b32 s34, v255, 34
	v_readlane_b32 s35, v255, 35
	v_readlane_b32 s36, v255, 36
	v_readlane_b32 s37, v255, 37
	v_readlane_b32 s38, v255, 38
	v_readlane_b32 s39, v255, 39
	v_readlane_b32 s40, v255, 40
	v_readlane_b32 s41, v255, 41
	v_readlane_b32 s42, v255, 42
	v_readlane_b32 s43, v255, 43
	v_readlane_b32 s44, v255, 44
	v_readlane_b32 s45, v255, 45
	v_readlane_b32 s46, v255, 46
	v_readlane_b32 s47, v255, 47
	v_readlane_b32 s48, v255, 48
	v_readlane_b32 s49, v255, 49
	v_readlane_b32 s50, v255, 50
	v_readlane_b32 s51, v255, 51
	v_readlane_b32 s52, v255, 52
	v_readlane_b32 s53, v255, 53
	v_readlane_b32 s54, v255, 54
	v_readlane_b32 s55, v255, 55
	v_readlane_b32 s56, v255, 56
	v_readlane_b32 s57, v255, 57
	v_readlane_b32 s58, v255, 58
	v_readlane_b32 s59, v255, 59
	v_readlane_b32 s60, v255, 60
	v_readlane_b32 s61, v255, 61
	v_readlane_b32 s62, v255, 62
	v_readlane_b32 s63, v255, 63
	v_readlane_b32 s64, v254, 0
	v_readlane_b32 s65, v254, 1
	v_readlane_b32 s66, v254, 2
	v_readlane_b32 s67, v254, 3
	v_readlane_b32 s68, v254, 4
	v_readlane_b32 s69, v254, 5
	v_readlane_b32 s70, v254, 6
	v_readlane_b32 s71, v254, 7
	v_readlane_b32 s72, v254, 8
	v_readlane_b32 s73, v254, 9
	v_readlane_b32 s74, v254, 10
	v_readlane_b32 s75, v254, 11
	v_readlane_b32 s76, v254, 12
	v_readlane_b32 s77, v254, 13
	.p2alignl 7, 3212836864
.LBB0_463:
	s_mov_b64 s[0:1], 0
